# attention: tile-1 K/V staging loads issued with the Q and tile-0 loads (counted wait), flat loads made global
# speedup vs baseline: 1.0108x; 1.0048x over previous
.LBB0_499:
	s_or_b32 s86, s15, s33
	s_lshl_b64 s[6:7], s[86:87], 1
	v_lshl_add_u64 v[16:17], v[180:181], 0, s[6:7]
	global_load_dwordx4 v[112:115], v[16:17], off offset:96
	global_load_dwordx4 v[116:119], v[16:17], off offset:64
	global_load_dwordx4 v[120:123], v[16:17], off offset:32
	global_load_dwordx4 v[124:127], v[16:17], off
	s_add_u32 s84, s8, s6
	s_addc_u32 s85, s9, s7
	s_mov_b64 s[6:7], s[84:85]
	s_nop 0
	v_lshl_add_u64 v[16:17], s[6:7], 0, v[182:183]
	s_add_u32 s6, s84, 0x20000
	s_addc_u32 s7, s85, 0
	global_load_dwordx4 v[16:19], v[16:17], off
	s_nop 0
	v_lshl_add_u64 v[20:21], s[6:7], 0, v[182:183]
	global_load_dwordx4 v[20:23], v[20:21], off
	s_mov_b64 s[6:7], s[90:91]
	v_lshl_add_u64 v[136:137], s[90:91], 0, v[184:185]
	global_load_dwordx4 v[128:131], v[136:137], off
	v_lshl_add_u64 v[138:139], s[0:1], 0, v[184:185]
	global_load_dwordx4 v[132:135], v[138:139], off
	s_add_u32 s100, s84, 0x40000
	s_addc_u32 s101, s85, 0
	v_lshl_add_u64 v[140:141], s[100:101], 0, v[182:183]
	global_load_dwordx4 v[144:147], v[140:141], off
	s_waitcnt vmcnt(3) lgkmcnt(0)
	ds_write_b128 v213, v[16:19]
	ds_write_b128 v213, v[20:23] offset:9216
	s_waitcnt lgkmcnt(0)
	s_barrier
	ds_read_b128 v[16:19], v208 offset:4608
	ds_read_b128 v[20:23], v208
	ds_read_b128 v[48:51], v208 offset:32
	ds_read_b128 v[52:55], v208 offset:4640
	ds_read_b128 v[56:59], v208 offset:64
	ds_read_b128 v[60:63], v208 offset:4672
	ds_read_b128 v[64:67], v208 offset:96
	ds_read_b128 v[68:71], v208 offset:4704
	s_waitcnt lgkmcnt(6)
	v_mfma_f32_32x32x16_bf16 v[32:47], v[20:23], v[124:127], 0
	s_waitcnt lgkmcnt(0)
	s_barrier
	v_mfma_f32_32x32x16_bf16 v[16:31], v[16:19], v[124:127], 0
	s_waitcnt lgkmcnt(5)
	v_mfma_f32_32x32x16_bf16 v[32:47], v[48:51], v[120:123], v[32:47]
	s_mov_b64 s[6:7], s[0:1]
	s_waitcnt lgkmcnt(4)
	v_mfma_f32_32x32x16_bf16 v[16:31], v[52:55], v[120:123], v[16:31]
	s_waitcnt lgkmcnt(3)
	v_mfma_f32_32x32x16_bf16 v[32:47], v[56:59], v[116:119], v[32:47]
	s_waitcnt lgkmcnt(2)
	v_mfma_f32_32x32x16_bf16 v[16:31], v[60:63], v[116:119], v[16:31]
	s_waitcnt lgkmcnt(1)
	v_mfma_f32_32x32x16_bf16 v[32:47], v[64:67], v[112:115], v[32:47]
	s_nop 0
	s_add_u32 s6, s84, 0x40000
	s_addc_u32 s7, s85, 0
	s_waitcnt lgkmcnt(0)
	v_mfma_f32_32x32x16_bf16 v[16:31], v[68:71], v[112:115], v[16:31]
	s_nop 0
	s_and_saveexec_b64 s[6:7], s[4:5]
	s_cbranch_execz .LBB0_501
	v_sub_f32_e32 v47, v47, v15
	v_sub_f32_e32 v46, v46, v14
	v_sub_f32_e32 v45, v45, v13
	v_sub_f32_e32 v44, v44, v12
	v_sub_f32_e32 v43, v43, v11
	v_sub_f32_e32 v42, v42, v10
	v_sub_f32_e32 v41, v41, v9
	v_sub_f32_e32 v40, v40, v8
	v_sub_f32_e32 v39, v39, v7
	v_sub_f32_e32 v38, v38, v6
	v_sub_f32_e32 v37, v37, v5
	v_sub_f32_e32 v36, v36, v4
	v_sub_f32_e32 v35, v35, v3
	v_sub_f32_e32 v34, v34, v2
	v_sub_f32_e32 v33, v33, v1
	v_sub_f32_e32 v32, v32, v0
	v_sub_f32_e32 v31, v31, v15
	v_sub_f32_e32 v30, v30, v14
	v_sub_f32_e32 v29, v29, v13
	v_sub_f32_e32 v28, v28, v12
	v_sub_f32_e32 v27, v27, v11
	v_sub_f32_e32 v26, v26, v10
	v_sub_f32_e32 v25, v25, v9
	v_sub_f32_e32 v24, v24, v8
	v_sub_f32_e32 v23, v23, v7
	v_sub_f32_e32 v22, v22, v6
	v_sub_f32_e32 v21, v21, v5
	v_sub_f32_e32 v20, v20, v4
	v_sub_f32_e32 v19, v19, v3
	v_sub_f32_e32 v18, v18, v2
	v_sub_f32_e32 v17, v17, v1
	v_sub_f32_e32 v16, v16, v0

.LBB0_505:
	v_add_f32_e32 v16, 0, v32
	v_add_f32_e32 v16, v33, v16
	v_add_f32_e32 v17, 0, v40
	v_add_f32_e32 v16, v34, v16
	v_add_f32_e32 v17, v41, v17
	v_add_f32_e32 v16, v35, v16
	v_add_f32_e32 v17, v42, v17
	v_add_f32_e32 v16, v36, v16
	v_add_f32_e32 v17, v43, v17
	v_add_f32_e32 v16, v37, v16
	v_add_f32_e32 v17, v44, v17
	v_add_f32_e32 v16, v38, v16
	v_add_f32_e32 v17, v45, v17
	v_add_f32_e32 v16, v39, v16
	v_add_f32_e32 v17, v46, v17
	v_add_f32_e32 v16, 0, v16
	v_add_f32_e32 v17, v47, v17
	v_add_f32_e32 v18, 0, v48
	v_add_f32_e32 v16, v17, v16
	v_add_f32_e32 v17, 0, v56
	v_add_f32_e32 v18, v49, v18
	v_add_f32_e32 v17, v57, v17
	v_add_f32_e32 v18, v50, v18
	v_add_f32_e32 v17, v58, v17
	v_add_f32_e32 v18, v51, v18
	v_add_f32_e32 v17, v59, v17
	v_add_f32_e32 v18, v52, v18
	v_add_f32_e32 v17, v60, v17
	v_add_f32_e32 v18, v53, v18
	v_add_f32_e32 v17, v61, v17
	v_add_f32_e32 v18, v54, v18
	s_waitcnt vmcnt(0)
	ds_write_b64 v216, v[128:129] offset:18432
	s_waitcnt lgkmcnt(0)
	ds_write_b64 v216, v[132:133] offset:27648
	ds_write2st64_b64 v217, v[130:131], v[134:135] offset0:36 offset1:54
	ds_write_b128 v213, v[144:147]
	v_add_f32_e32 v17, v62, v17
	v_add_f32_e32 v18, v55, v18
	s_waitcnt lgkmcnt(0)
	s_barrier
	v_add_f32_e32 v17, v63, v17
	v_add_f32_e32 v16, v18, v16
	v_mov_b32_e32 v31, 0
	v_cvt_pk_bf16_f32 v160, v32, v33
	v_cvt_pk_bf16_f32 v161, v34, v35
	v_cvt_pk_bf16_f32 v162, v36, v37
	v_cvt_pk_bf16_f32 v163, v38, v39
	v_cvt_pk_bf16_f32 v148, v40, v41
	v_cvt_pk_bf16_f32 v149, v42, v43
	v_cvt_pk_bf16_f32 v150, v44, v45
	v_cvt_pk_bf16_f32 v151, v46, v47
	v_cvt_pk_bf16_f32 v152, v48, v49
	v_cvt_pk_bf16_f32 v153, v50, v51
	v_cvt_pk_bf16_f32 v154, v52, v53
	v_cvt_pk_bf16_f32 v155, v54, v55
	v_add_f32_e32 v193, v17, v16
	v_cvt_pk_bf16_f32 v156, v56, v57
	v_cvt_pk_bf16_f32 v157, v58, v59
	v_cvt_pk_bf16_f32 v158, v60, v61
	v_cvt_pk_bf16_f32 v159, v62, v63
	s_andn2_b64 vcc, exec, s[2:3]
	s_cbranch_vccnz .LBB0_512
	v_mov_b32_e32 v32, 0
	s_mov_b32 s93, 0
	s_movk_i32 s15, 0x80
	s_mov_b64 s[6:7], 0x80
	v_mov_b32_e32 v33, v32
	v_mov_b32_e32 v34, v32
	v_mov_b32_e32 v35, v32
	v_mov_b32_e32 v36, v32
	v_mov_b32_e32 v37, v32
	v_mov_b32_e32 v38, v32
	v_mov_b32_e32 v39, v32
	v_mov_b32_e32 v40, v32
	v_mov_b32_e32 v41, v32
	v_mov_b32_e32 v42, v32
	v_mov_b32_e32 v43, v32
	v_mov_b32_e32 v44, v32
	v_mov_b32_e32 v45, v32
	v_mov_b32_e32 v46, v32
	v_mov_b32_e32 v47, v32
	v_mov_b32_e32 v64, v32
	v_mov_b32_e32 v65, v32
	v_mov_b32_e32 v66, v32
	v_mov_b32_e32 v67, v32
	v_mov_b32_e32 v68, v32
	v_mov_b32_e32 v69, v32
	v_mov_b32_e32 v70, v32
	v_mov_b32_e32 v71, v32
	v_mov_b32_e32 v72, v32
	v_mov_b32_e32 v73, v32
	v_mov_b32_e32 v74, v32
	v_mov_b32_e32 v75, v32
	v_mov_b32_e32 v76, v32
	v_mov_b32_e32 v77, v32
	v_mov_b32_e32 v78, v32
	v_mov_b32_e32 v79, v32
	v_mov_b32_e32 v48, v32
	v_mov_b32_e32 v49, v32
	v_mov_b32_e32 v50, v32
	v_mov_b32_e32 v51, v32
	v_mov_b32_e32 v52, v32
	v_mov_b32_e32 v53, v32
	v_mov_b32_e32 v54, v32
	v_mov_b32_e32 v55, v32
	v_mov_b32_e32 v56, v32
	v_mov_b32_e32 v57, v32
	v_mov_b32_e32 v58, v32
	v_mov_b32_e32 v59, v32
	v_mov_b32_e32 v60, v32
	v_mov_b32_e32 v61, v32
	v_mov_b32_e32 v62, v32
	v_mov_b32_e32 v63, v32
	v_mov_b32_e32 v16, v32
	v_mov_b32_e32 v17, v32
	v_mov_b32_e32 v18, v32
	v_mov_b32_e32 v19, v32
	v_mov_b32_e32 v20, v32
	v_mov_b32_e32 v21, v32
	v_mov_b32_e32 v22, v32
	v_mov_b32_e32 v23, v32
	v_mov_b32_e32 v24, v32
	v_mov_b32_e32 v25, v32
	v_mov_b32_e32 v26, v32
	v_mov_b32_e32 v27, v32
	v_mov_b32_e32 v28, v32
	v_mov_b32_e32 v29, v32
	v_mov_b32_e32 v30, v32
	v_mov_b32_e32 v31, v32
	v_mov_b32_e32 v142, 0
	s_branch .LBB0_508
	.p2align 6
	s_nop 0
	s_nop 0
	s_nop 0
	s_nop 0
	s_nop 0
	s_nop 0
	s_nop 0
	s_nop 0
	s_nop 0
	s_nop 0
	s_nop 0
	s_nop 0

.LBB0_533:
	s_or_b32 s86, s15, s33
	s_lshl_b64 s[6:7], s[86:87], 1
	v_lshl_add_u64 v[16:17], v[180:181], 0, s[6:7]
	global_load_dwordx4 v[112:115], v[16:17], off offset:96
	global_load_dwordx4 v[116:119], v[16:17], off offset:64
	global_load_dwordx4 v[120:123], v[16:17], off offset:32
	global_load_dwordx4 v[124:127], v[16:17], off
	s_add_u32 s96, s8, s6
	s_addc_u32 s97, s9, s7
	s_mov_b64 s[6:7], s[96:97]
	s_nop 0
	v_lshl_add_u64 v[16:17], s[6:7], 0, v[182:183]
	s_add_u32 s6, s96, 0x20000
	s_addc_u32 s7, s97, 0
	global_load_dwordx4 v[16:19], v[16:17], off
	s_nop 0
	v_lshl_add_u64 v[20:21], s[6:7], 0, v[182:183]
	global_load_dwordx4 v[20:23], v[20:21], off
	s_mov_b64 s[6:7], s[90:91]
	v_lshl_add_u64 v[136:137], s[90:91], 0, v[184:185]
	global_load_dwordx4 v[128:131], v[136:137], off
	v_lshl_add_u64 v[138:139], s[0:1], 0, v[184:185]
	global_load_dwordx4 v[132:135], v[138:139], off
	s_add_u32 s100, s96, 0x40000
	s_addc_u32 s101, s97, 0
	v_lshl_add_u64 v[140:141], s[100:101], 0, v[182:183]
	global_load_dwordx4 v[144:147], v[140:141], off
	s_waitcnt vmcnt(3) lgkmcnt(0)
	ds_write_b128 v213, v[16:19]
	ds_write_b128 v213, v[20:23] offset:9216
	s_waitcnt lgkmcnt(0)
	s_barrier
	ds_read_b128 v[16:19], v208 offset:4608
	ds_read_b128 v[20:23], v208
	ds_read_b128 v[48:51], v208 offset:32
	ds_read_b128 v[52:55], v208 offset:4640
	ds_read_b128 v[56:59], v208 offset:64
	ds_read_b128 v[60:63], v208 offset:4672
	ds_read_b128 v[64:67], v208 offset:96
	ds_read_b128 v[68:71], v208 offset:4704
	s_waitcnt lgkmcnt(6)
	v_mfma_f32_32x32x16_bf16 v[32:47], v[20:23], v[124:127], 0
	s_waitcnt lgkmcnt(0)
	s_barrier
	v_mfma_f32_32x32x16_bf16 v[16:31], v[16:19], v[124:127], 0
	s_waitcnt lgkmcnt(5)
	v_mfma_f32_32x32x16_bf16 v[32:47], v[48:51], v[120:123], v[32:47]
	s_mov_b64 s[6:7], s[0:1]
	s_waitcnt lgkmcnt(4)
	v_mfma_f32_32x32x16_bf16 v[16:31], v[52:55], v[120:123], v[16:31]
	s_waitcnt lgkmcnt(3)
	v_mfma_f32_32x32x16_bf16 v[32:47], v[56:59], v[116:119], v[32:47]
	s_waitcnt lgkmcnt(2)
	v_mfma_f32_32x32x16_bf16 v[16:31], v[60:63], v[116:119], v[16:31]
	s_waitcnt lgkmcnt(1)
	v_mfma_f32_32x32x16_bf16 v[32:47], v[64:67], v[112:115], v[32:47]
	s_nop 0
	s_add_u32 s6, s96, 0x40000
	s_addc_u32 s7, s97, 0
	s_waitcnt lgkmcnt(0)
	v_mfma_f32_32x32x16_bf16 v[16:31], v[68:71], v[112:115], v[16:31]
	s_nop 0
	s_and_saveexec_b64 s[6:7], s[4:5]
	s_cbranch_execz .LBB0_535
	v_sub_f32_e32 v47, v47, v15
	v_sub_f32_e32 v46, v46, v14
	v_sub_f32_e32 v45, v45, v13
	v_sub_f32_e32 v44, v44, v12
	v_sub_f32_e32 v43, v43, v11
	v_sub_f32_e32 v42, v42, v10
	v_sub_f32_e32 v41, v41, v9
	v_sub_f32_e32 v40, v40, v8
	v_sub_f32_e32 v39, v39, v7
	v_sub_f32_e32 v38, v38, v6
	v_sub_f32_e32 v37, v37, v5
	v_sub_f32_e32 v36, v36, v4
	v_sub_f32_e32 v35, v35, v3
	v_sub_f32_e32 v34, v34, v2
	v_sub_f32_e32 v33, v33, v1
	v_sub_f32_e32 v32, v32, v0
	v_sub_f32_e32 v31, v31, v15
	v_sub_f32_e32 v30, v30, v14
	v_sub_f32_e32 v29, v29, v13
	v_sub_f32_e32 v28, v28, v12
	v_sub_f32_e32 v27, v27, v11
	v_sub_f32_e32 v26, v26, v10
	v_sub_f32_e32 v25, v25, v9
	v_sub_f32_e32 v24, v24, v8
	v_sub_f32_e32 v23, v23, v7
	v_sub_f32_e32 v22, v22, v6
	v_sub_f32_e32 v21, v21, v5
	v_sub_f32_e32 v20, v20, v4
	v_sub_f32_e32 v19, v19, v3
	v_sub_f32_e32 v18, v18, v2
	v_sub_f32_e32 v17, v17, v1
	v_sub_f32_e32 v16, v16, v0

.LBB0_539:
	v_add_f32_e32 v16, 0, v32
	v_add_f32_e32 v16, v33, v16
	v_add_f32_e32 v17, 0, v40
	v_add_f32_e32 v16, v34, v16
	v_add_f32_e32 v17, v41, v17
	v_add_f32_e32 v16, v35, v16
	v_add_f32_e32 v17, v42, v17
	v_add_f32_e32 v16, v36, v16
	v_add_f32_e32 v17, v43, v17
	v_add_f32_e32 v16, v37, v16
	v_add_f32_e32 v17, v44, v17
	v_add_f32_e32 v16, v38, v16
	v_add_f32_e32 v17, v45, v17
	v_add_f32_e32 v16, v39, v16
	v_add_f32_e32 v17, v46, v17
	v_add_f32_e32 v16, 0, v16
	v_add_f32_e32 v17, v47, v17
	v_add_f32_e32 v18, 0, v48
	v_add_f32_e32 v16, v17, v16
	v_add_f32_e32 v17, 0, v56
	v_add_f32_e32 v18, v49, v18
	v_add_f32_e32 v17, v57, v17
	v_add_f32_e32 v18, v50, v18
	v_add_f32_e32 v17, v58, v17
	v_add_f32_e32 v18, v51, v18
	v_add_f32_e32 v17, v59, v17
	v_add_f32_e32 v18, v52, v18
	v_add_f32_e32 v17, v60, v17
	v_add_f32_e32 v18, v53, v18
	v_add_f32_e32 v17, v61, v17
	v_add_f32_e32 v18, v54, v18
	s_waitcnt vmcnt(0)
	ds_write_b64 v216, v[128:129] offset:18432
	s_waitcnt lgkmcnt(0)
	ds_write_b64 v216, v[132:133] offset:27648
	ds_write2st64_b64 v217, v[130:131], v[134:135] offset0:36 offset1:54
	ds_write_b128 v213, v[144:147]
	v_add_f32_e32 v17, v62, v17
	v_add_f32_e32 v18, v55, v18
	s_waitcnt lgkmcnt(0)
	s_barrier
	v_add_f32_e32 v17, v63, v17
	v_add_f32_e32 v16, v18, v16
	v_mov_b32_e32 v31, 0
	v_cvt_pk_bf16_f32 v160, v32, v33
	v_cvt_pk_bf16_f32 v161, v34, v35
	v_cvt_pk_bf16_f32 v162, v36, v37
	v_cvt_pk_bf16_f32 v163, v38, v39
	v_cvt_pk_bf16_f32 v148, v40, v41
	v_cvt_pk_bf16_f32 v149, v42, v43
	v_cvt_pk_bf16_f32 v150, v44, v45
	v_cvt_pk_bf16_f32 v151, v46, v47
	v_cvt_pk_bf16_f32 v152, v48, v49
	v_cvt_pk_bf16_f32 v153, v50, v51
	v_cvt_pk_bf16_f32 v154, v52, v53
	v_cvt_pk_bf16_f32 v155, v54, v55
	v_add_f32_e32 v193, v17, v16
	v_cvt_pk_bf16_f32 v156, v56, v57
	v_cvt_pk_bf16_f32 v157, v58, v59
	v_cvt_pk_bf16_f32 v158, v60, v61
	v_cvt_pk_bf16_f32 v159, v62, v63
	s_andn2_b64 vcc, exec, s[80:81]
	s_cbranch_vccnz .LBB0_546
	v_mov_b32_e32 v32, 0
	s_mov_b32 s77, 0
	s_movk_i32 s15, 0x80
	s_mov_b64 s[6:7], 0x80
	v_mov_b32_e32 v33, v32
	v_mov_b32_e32 v34, v32
	v_mov_b32_e32 v35, v32
	v_mov_b32_e32 v36, v32
	v_mov_b32_e32 v37, v32
	v_mov_b32_e32 v38, v32
	v_mov_b32_e32 v39, v32
	v_mov_b32_e32 v40, v32
	v_mov_b32_e32 v41, v32
	v_mov_b32_e32 v42, v32
	v_mov_b32_e32 v43, v32
	v_mov_b32_e32 v44, v32
	v_mov_b32_e32 v45, v32
	v_mov_b32_e32 v46, v32
	v_mov_b32_e32 v47, v32
	v_mov_b32_e32 v64, v32
	v_mov_b32_e32 v65, v32
	v_mov_b32_e32 v66, v32
	v_mov_b32_e32 v67, v32
	v_mov_b32_e32 v68, v32
	v_mov_b32_e32 v69, v32
	v_mov_b32_e32 v70, v32
	v_mov_b32_e32 v71, v32
	v_mov_b32_e32 v72, v32
	v_mov_b32_e32 v73, v32
	v_mov_b32_e32 v74, v32
	v_mov_b32_e32 v75, v32
	v_mov_b32_e32 v76, v32
	v_mov_b32_e32 v77, v32
	v_mov_b32_e32 v78, v32
	v_mov_b32_e32 v79, v32
	v_mov_b32_e32 v48, v32
	v_mov_b32_e32 v49, v32
	v_mov_b32_e32 v50, v32
	v_mov_b32_e32 v51, v32
	v_mov_b32_e32 v52, v32
	v_mov_b32_e32 v53, v32
	v_mov_b32_e32 v54, v32
	v_mov_b32_e32 v55, v32
	v_mov_b32_e32 v56, v32
	v_mov_b32_e32 v57, v32
	v_mov_b32_e32 v58, v32
	v_mov_b32_e32 v59, v32
	v_mov_b32_e32 v60, v32
	v_mov_b32_e32 v61, v32
	v_mov_b32_e32 v62, v32
	v_mov_b32_e32 v63, v32
	v_mov_b32_e32 v16, v32
	v_mov_b32_e32 v17, v32
	v_mov_b32_e32 v18, v32
	v_mov_b32_e32 v19, v32
	v_mov_b32_e32 v20, v32
	v_mov_b32_e32 v21, v32
	v_mov_b32_e32 v22, v32
	v_mov_b32_e32 v23, v32
	v_mov_b32_e32 v24, v32
	v_mov_b32_e32 v25, v32
	v_mov_b32_e32 v26, v32
	v_mov_b32_e32 v27, v32
	v_mov_b32_e32 v28, v32
	v_mov_b32_e32 v29, v32
	v_mov_b32_e32 v30, v32
	v_mov_b32_e32 v31, v32
	v_mov_b32_e32 v142, 0
	s_branch .LBB0_542
	.p2align 6
	s_nop 0
	s_nop 0
	s_nop 0
	s_nop 0
